# GEMM1 gate epilogue regenerated: all VALU first, then 16 full stores back-to-back (control); + no entry grid.sync
# speedup vs baseline: 1.0261x; 1.0146x over previous
; __device__ __forceinline__ float sigm(float v) { return __builtin_amdgcn_rcpf(1.0f + __builtin_amdgcn_exp2f(-LOG2E * v)); }
; __device__ __forceinline__ unsigned cvt_pk_bf16(float lo, float hi) { f32x2_t v = {lo, hi}; bf16x2_t b = __builtin_convertvector(v, bf16x2_t); return __builtin_bit_cast(unsigned, b); }
; #define EPI_FENCE() asm volatile("" ::: "memory")
; #define EPI_LANE() int t__ = threadIdx.x; asm volatile("" : "+v"(t__)); const int wid__ = __builtin_amdgcn_readfirstlane(t__ >> 6); wr = wid__ >> 2; wc = wid__ & 3; fr = t__ & 15; fq = (t__ & 63) >> 4
; template <int MODE> __device__ __forceinline__ float actf(float v) {
;     if (MODE == 1) return v * sigm(v);
;     if (MODE == 2) return fminf(1.0f + __builtin_amdgcn_exp2f(-LOG2E * v), 1e30f);
;     if (MODE == 3) return v * QSCALE;
;     return v;
; }
;     template <int MODE> __device__ __forceinline__ void run(const f32x4 (&acc)[2][2][4][2], const Unit& u, int wr, int wc, int fr, int fq) const {
;         EPI_LANE();
;         const int pn = u.pn, colt = pn * BM, t = colt >> 9;
;         char* base = (MODE == 2) ? (char*)(O + (size_t)6 * ((size_t)MTOK * 512)) + ((size_t)(((pn - 12) * 128 + u.pm) * 8 + wid__)) * 16384
;                                  : (char*)(O + (size_t)t * ((size_t)MTOK * 512) + (size_t)u.pm * BM * 512 + (colt & 511));
;         unsigned off0 = (MODE == 2) ? (unsigned)((t__ & 63) * 16) : (unsigned)((wr * 64 + fr) * 512 + wc * 32 + 8 * fq) * 2u; asm volatile("" : "+v"(off0));
; #pragma unroll
;         for (int bj = 0; bj < 2; ++bj) {
; #pragma unroll
;             for (int ai = 0; ai < 2; ++ai)
; #pragma unroll
;                 for (int m = 0; m < 4; ++m) { const unsigned off = off0 + ((MODE == 2) ? (unsigned)(((ai * 4 + m) * 2 + bj) * 1024) : (unsigned)((ai * HALF + m * 16) * 512 + bj * HALF) * 2u);
;                     const f32x4 v0 = acc[ai][bj][m][0], v1 = acc[ai][bj][m][1];
;                     u32x4 w; w.x = cvt_pk_bf16(actf<MODE>(v0[0]), actf<MODE>(v0[1])); w.y = cvt_pk_bf16(actf<MODE>(v0[2]), actf<MODE>(v0[3]));
;                     w.z = cvt_pk_bf16(actf<MODE>(v1[0]), actf<MODE>(v1[1])); w.w = cvt_pk_bf16(actf<MODE>(v1[2]), actf<MODE>(v1[3]));
;                     *(u32x4*)(base + off) = w; }
;             EPI_FENCE();
;         }
.LBB0_403:
	v_mov_b32_e32 v142, v212
	s_lshl_b32 s60, s72, 7
	s_add_i32 s60, s60, s54
	v_readfirstlane_b32 s55, v142
	s_lshl_b32 s54, s60, 3
	s_ashr_i32 s55, s55, 6
	s_add_i32 s54, s54, s55
	s_addk_i32 s54, 0xd000
	s_ashr_i32 s55, s54, 31
	s_lshl_b64 s[54:55], s[54:55], 14
	v_lshlrev_b32_e32 v142, 4, v142
	s_add_u32 s54, s33, s54
	s_addc_u32 s55, s37, s55
	v_and_b32_e32 v142, 0x3f0, v142
	v_add_u32_e32 v144, 0x400, v142
	v_add_u32_e32 v145, 0x800, v142
	v_add_u32_e32 v146, 0xc00, v142
	v_add_u32_e32 v147, 0x1000, v142
	v_add_u32_e32 v148, 0x1400, v142
	v_add_u32_e32 v149, 0x1800, v142
	v_add_u32_e32 v150, 0x1c00, v142
	v_add_u32_e32 v151, 0x2000, v142
	v_add_u32_e32 v152, 0x2400, v142
	v_add_u32_e32 v153, 0x2800, v142
	v_add_u32_e32 v154, 0x2c00, v142
	v_add_u32_e32 v155, 0x3000, v142
	v_add_u32_e32 v156, 0x3400, v142
	v_add_u32_e32 v157, 0x3800, v142
	v_add_u32_e32 v158, 0x3c00, v142
	v_mul_f32_e32 v126, 0xbfb8aa3b, v126
	v_mul_f32_e32 v127, 0xbfb8aa3b, v127
	v_mul_f32_e32 v128, 0xbfb8aa3b, v128
	v_mul_f32_e32 v129, 0xbfb8aa3b, v129
	v_mul_f32_e32 v122, 0xbfb8aa3b, v122
	v_mul_f32_e32 v123, 0xbfb8aa3b, v123
	v_mul_f32_e32 v124, 0xbfb8aa3b, v124
	v_mul_f32_e32 v125, 0xbfb8aa3b, v125
	v_exp_f32_e32 v126, v126
	v_exp_f32_e32 v127, v127
	v_exp_f32_e32 v128, v128
	v_exp_f32_e32 v129, v129
	v_exp_f32_e32 v122, v122
	v_exp_f32_e32 v123, v123
	v_exp_f32_e32 v124, v124
	v_exp_f32_e32 v125, v125
	v_add_f32_e32 v126, 1.0, v126
	v_add_f32_e32 v127, 1.0, v127
	v_add_f32_e32 v128, 1.0, v128
	v_add_f32_e32 v129, 1.0, v129
	v_add_f32_e32 v122, 1.0, v122
	v_add_f32_e32 v123, 1.0, v123
	v_add_f32_e32 v124, 1.0, v124
	v_add_f32_e32 v125, 1.0, v125
	v_min_f32_e32 v126, 0x7149f2ca, v126
	v_min_f32_e32 v127, 0x7149f2ca, v127
	v_min_f32_e32 v128, 0x7149f2ca, v128
	v_min_f32_e32 v129, 0x7149f2ca, v129
	v_min_f32_e32 v122, 0x7149f2ca, v122
	v_min_f32_e32 v123, 0x7149f2ca, v123
	v_min_f32_e32 v124, 0x7149f2ca, v124
	v_min_f32_e32 v125, 0x7149f2ca, v125
	v_cvt_pk_bf16_f32 v126, v126, v127
	v_cvt_pk_bf16_f32 v127, v128, v129
	v_cvt_pk_bf16_f32 v128, v122, v123
	v_cvt_pk_bf16_f32 v129, v124, v125
	v_mul_f32_e32 v68, 0xbfb8aa3b, v68
	v_mul_f32_e32 v69, 0xbfb8aa3b, v69
	v_mul_f32_e32 v70, 0xbfb8aa3b, v70
	v_mul_f32_e32 v71, 0xbfb8aa3b, v71
	v_mul_f32_e32 v64, 0xbfb8aa3b, v64
	v_mul_f32_e32 v65, 0xbfb8aa3b, v65
	v_mul_f32_e32 v66, 0xbfb8aa3b, v66
	v_mul_f32_e32 v67, 0xbfb8aa3b, v67
	v_exp_f32_e32 v68, v68
	v_exp_f32_e32 v69, v69
	v_exp_f32_e32 v70, v70
	v_exp_f32_e32 v71, v71
	v_exp_f32_e32 v64, v64
	v_exp_f32_e32 v65, v65
	v_exp_f32_e32 v66, v66
	v_exp_f32_e32 v67, v67
	v_add_f32_e32 v68, 1.0, v68
	v_add_f32_e32 v69, 1.0, v69
	v_add_f32_e32 v70, 1.0, v70
	v_add_f32_e32 v71, 1.0, v71
	v_add_f32_e32 v64, 1.0, v64
	v_add_f32_e32 v65, 1.0, v65
	v_add_f32_e32 v66, 1.0, v66
	v_add_f32_e32 v67, 1.0, v67
	v_min_f32_e32 v68, 0x7149f2ca, v68
	v_min_f32_e32 v69, 0x7149f2ca, v69
	v_min_f32_e32 v70, 0x7149f2ca, v70
	v_min_f32_e32 v71, 0x7149f2ca, v71
	v_min_f32_e32 v64, 0x7149f2ca, v64
	v_min_f32_e32 v65, 0x7149f2ca, v65
	v_min_f32_e32 v66, 0x7149f2ca, v66
	v_min_f32_e32 v67, 0x7149f2ca, v67
	v_cvt_pk_bf16_f32 v68, v68, v69
	v_cvt_pk_bf16_f32 v69, v70, v71
	v_cvt_pk_bf16_f32 v70, v64, v65
	v_cvt_pk_bf16_f32 v71, v66, v67
	v_mul_f32_e32 v118, 0xbfb8aa3b, v118
	v_mul_f32_e32 v119, 0xbfb8aa3b, v119
	v_mul_f32_e32 v120, 0xbfb8aa3b, v120
	v_mul_f32_e32 v121, 0xbfb8aa3b, v121
	v_mul_f32_e32 v114, 0xbfb8aa3b, v114
	v_mul_f32_e32 v115, 0xbfb8aa3b, v115
	v_mul_f32_e32 v116, 0xbfb8aa3b, v116
	v_mul_f32_e32 v117, 0xbfb8aa3b, v117
	v_exp_f32_e32 v118, v118
	v_exp_f32_e32 v119, v119
	v_exp_f32_e32 v120, v120
	v_exp_f32_e32 v121, v121
	v_exp_f32_e32 v114, v114
	v_exp_f32_e32 v115, v115
	v_exp_f32_e32 v116, v116
	v_exp_f32_e32 v117, v117
	v_add_f32_e32 v118, 1.0, v118
	v_add_f32_e32 v119, 1.0, v119
	v_add_f32_e32 v120, 1.0, v120
	v_add_f32_e32 v121, 1.0, v121
	v_add_f32_e32 v114, 1.0, v114
	v_add_f32_e32 v115, 1.0, v115
	v_add_f32_e32 v116, 1.0, v116
	v_add_f32_e32 v117, 1.0, v117
	v_min_f32_e32 v118, 0x7149f2ca, v118
	v_min_f32_e32 v119, 0x7149f2ca, v119
	v_min_f32_e32 v120, 0x7149f2ca, v120
	v_min_f32_e32 v121, 0x7149f2ca, v121
	v_min_f32_e32 v114, 0x7149f2ca, v114
	v_min_f32_e32 v115, 0x7149f2ca, v115
	v_min_f32_e32 v116, 0x7149f2ca, v116
	v_min_f32_e32 v117, 0x7149f2ca, v117
	v_cvt_pk_bf16_f32 v118, v118, v119
	v_cvt_pk_bf16_f32 v119, v120, v121
	v_cvt_pk_bf16_f32 v120, v114, v115
	v_cvt_pk_bf16_f32 v121, v116, v117
	v_mul_f32_e32 v60, 0xbfb8aa3b, v60
	v_mul_f32_e32 v61, 0xbfb8aa3b, v61
	v_mul_f32_e32 v62, 0xbfb8aa3b, v62
	v_mul_f32_e32 v63, 0xbfb8aa3b, v63
	v_mul_f32_e32 v56, 0xbfb8aa3b, v56
	v_mul_f32_e32 v57, 0xbfb8aa3b, v57
	v_mul_f32_e32 v58, 0xbfb8aa3b, v58
	v_mul_f32_e32 v59, 0xbfb8aa3b, v59
	v_exp_f32_e32 v60, v60
	v_exp_f32_e32 v61, v61
	v_exp_f32_e32 v62, v62
	v_exp_f32_e32 v63, v63
	v_exp_f32_e32 v56, v56
	v_exp_f32_e32 v57, v57
	v_exp_f32_e32 v58, v58
	v_exp_f32_e32 v59, v59
	v_add_f32_e32 v60, 1.0, v60
	v_add_f32_e32 v61, 1.0, v61
	v_add_f32_e32 v62, 1.0, v62
	v_add_f32_e32 v63, 1.0, v63
	v_add_f32_e32 v56, 1.0, v56
	v_add_f32_e32 v57, 1.0, v57
	v_add_f32_e32 v58, 1.0, v58
	v_add_f32_e32 v59, 1.0, v59
	v_min_f32_e32 v60, 0x7149f2ca, v60
	v_min_f32_e32 v61, 0x7149f2ca, v61
	v_min_f32_e32 v62, 0x7149f2ca, v62
	v_min_f32_e32 v63, 0x7149f2ca, v63
	v_min_f32_e32 v56, 0x7149f2ca, v56
	v_min_f32_e32 v57, 0x7149f2ca, v57
	v_min_f32_e32 v58, 0x7149f2ca, v58
	v_min_f32_e32 v59, 0x7149f2ca, v59
	v_cvt_pk_bf16_f32 v60, v60, v61
	v_cvt_pk_bf16_f32 v61, v62, v63
	v_cvt_pk_bf16_f32 v62, v56, v57
	v_cvt_pk_bf16_f32 v63, v58, v59
	v_mul_f32_e32 v110, 0xbfb8aa3b, v110
	v_mul_f32_e32 v111, 0xbfb8aa3b, v111
; __device__ __forceinline__ float sigm(float v) { return __builtin_amdgcn_rcpf(1.0f + __builtin_amdgcn_exp2f(-LOG2E * v)); }
; __device__ __forceinline__ unsigned cvt_pk_bf16(float lo, float hi) { f32x2_t v = {lo, hi}; bf16x2_t b = __builtin_convertvector(v, bf16x2_t); return __builtin_bit_cast(unsigned, b); }
; #define EPI_FENCE() asm volatile("" ::: "memory")
; #define EPI_LANE() int t__ = threadIdx.x; asm volatile("" : "+v"(t__)); const int wid__ = __builtin_amdgcn_readfirstlane(t__ >> 6); wr = wid__ >> 2; wc = wid__ & 3; fr = t__ & 15; fq = (t__ & 63) >> 4
; template <int MODE> __device__ __forceinline__ float actf(float v) {
;     if (MODE == 1) return v * sigm(v);
;     if (MODE == 2) return fminf(1.0f + __builtin_amdgcn_exp2f(-LOG2E * v), 1e30f);
;     if (MODE == 3) return v * QSCALE;
;     return v;
; }
;     template <int MODE> __device__ __forceinline__ void run(const f32x4 (&acc)[2][2][4][2], const Unit& u, int wr, int wc, int fr, int fq) const {
;         EPI_LANE();
;         const int pn = u.pn, colt = pn * BM, t = colt >> 9;
;         char* base = (MODE == 2) ? (char*)(O + (size_t)6 * ((size_t)MTOK * 512)) + ((size_t)(((pn - 12) * 128 + u.pm) * 8 + wid__)) * 16384
;                                  : (char*)(O + (size_t)t * ((size_t)MTOK * 512) + (size_t)u.pm * BM * 512 + (colt & 511));
;         unsigned off0 = (MODE == 2) ? (unsigned)((t__ & 63) * 16) : (unsigned)((wr * 64 + fr) * 512 + wc * 32 + 8 * fq) * 2u; asm volatile("" : "+v"(off0));
; #pragma unroll
;         for (int bj = 0; bj < 2; ++bj) {
; #pragma unroll
;             for (int ai = 0; ai < 2; ++ai)
; #pragma unroll
;                 for (int m = 0; m < 4; ++m) { const unsigned off = off0 + ((MODE == 2) ? (unsigned)(((ai * 4 + m) * 2 + bj) * 1024) : (unsigned)((ai * HALF + m * 16) * 512 + bj * HALF) * 2u);
;                     const f32x4 v0 = acc[ai][bj][m][0], v1 = acc[ai][bj][m][1];
;                     u32x4 w; w.x = cvt_pk_bf16(actf<MODE>(v0[0]), actf<MODE>(v0[1])); w.y = cvt_pk_bf16(actf<MODE>(v0[2]), actf<MODE>(v0[3]));
;                     w.z = cvt_pk_bf16(actf<MODE>(v1[0]), actf<MODE>(v1[1])); w.w = cvt_pk_bf16(actf<MODE>(v1[2]), actf<MODE>(v1[3]));
;                     *(u32x4*)(base + off) = w; }
;             EPI_FENCE();
;         }
	v_mul_f32_e32 v112, 0xbfb8aa3b, v112
	v_mul_f32_e32 v113, 0xbfb8aa3b, v113
	v_mul_f32_e32 v106, 0xbfb8aa3b, v106
	v_mul_f32_e32 v107, 0xbfb8aa3b, v107
	v_mul_f32_e32 v108, 0xbfb8aa3b, v108
	v_mul_f32_e32 v109, 0xbfb8aa3b, v109
	v_exp_f32_e32 v110, v110
	v_exp_f32_e32 v111, v111
	v_exp_f32_e32 v112, v112
	v_exp_f32_e32 v113, v113
	v_exp_f32_e32 v106, v106
	v_exp_f32_e32 v107, v107
	v_exp_f32_e32 v108, v108
	v_exp_f32_e32 v109, v109
	v_add_f32_e32 v110, 1.0, v110
	v_add_f32_e32 v111, 1.0, v111
	v_add_f32_e32 v112, 1.0, v112
	v_add_f32_e32 v113, 1.0, v113
	v_add_f32_e32 v106, 1.0, v106
	v_add_f32_e32 v107, 1.0, v107
	v_add_f32_e32 v108, 1.0, v108
	v_add_f32_e32 v109, 1.0, v109
	v_min_f32_e32 v110, 0x7149f2ca, v110
	v_min_f32_e32 v111, 0x7149f2ca, v111
	v_min_f32_e32 v112, 0x7149f2ca, v112
	v_min_f32_e32 v113, 0x7149f2ca, v113
	v_min_f32_e32 v106, 0x7149f2ca, v106
	v_min_f32_e32 v107, 0x7149f2ca, v107
	v_min_f32_e32 v108, 0x7149f2ca, v108
	v_min_f32_e32 v109, 0x7149f2ca, v109
	v_cvt_pk_bf16_f32 v110, v110, v111
	v_cvt_pk_bf16_f32 v111, v112, v113
	v_cvt_pk_bf16_f32 v112, v106, v107
	v_cvt_pk_bf16_f32 v113, v108, v109
	v_mul_f32_e32 v52, 0xbfb8aa3b, v52
	v_mul_f32_e32 v53, 0xbfb8aa3b, v53
	v_mul_f32_e32 v54, 0xbfb8aa3b, v54
	v_mul_f32_e32 v55, 0xbfb8aa3b, v55
	v_mul_f32_e32 v48, 0xbfb8aa3b, v48
	v_mul_f32_e32 v49, 0xbfb8aa3b, v49
	v_mul_f32_e32 v50, 0xbfb8aa3b, v50
	v_mul_f32_e32 v51, 0xbfb8aa3b, v51
	v_exp_f32_e32 v52, v52
	v_exp_f32_e32 v53, v53
	v_exp_f32_e32 v54, v54
	v_exp_f32_e32 v55, v55
	v_exp_f32_e32 v48, v48
	v_exp_f32_e32 v49, v49
	v_exp_f32_e32 v50, v50
	v_exp_f32_e32 v51, v51
	v_add_f32_e32 v52, 1.0, v52
	v_add_f32_e32 v53, 1.0, v53
	v_add_f32_e32 v54, 1.0, v54
	v_add_f32_e32 v55, 1.0, v55
	v_add_f32_e32 v48, 1.0, v48
	v_add_f32_e32 v49, 1.0, v49
	v_add_f32_e32 v50, 1.0, v50
	v_add_f32_e32 v51, 1.0, v51
	v_min_f32_e32 v52, 0x7149f2ca, v52
	v_min_f32_e32 v53, 0x7149f2ca, v53
	v_min_f32_e32 v54, 0x7149f2ca, v54
	v_min_f32_e32 v55, 0x7149f2ca, v55
	v_min_f32_e32 v48, 0x7149f2ca, v48
	v_min_f32_e32 v49, 0x7149f2ca, v49
	v_min_f32_e32 v50, 0x7149f2ca, v50
	v_min_f32_e32 v51, 0x7149f2ca, v51
	v_cvt_pk_bf16_f32 v52, v52, v53
	v_cvt_pk_bf16_f32 v53, v54, v55
	v_cvt_pk_bf16_f32 v54, v48, v49
	v_cvt_pk_bf16_f32 v55, v50, v51
	v_mul_f32_e32 v102, 0xbfb8aa3b, v102
	v_mul_f32_e32 v103, 0xbfb8aa3b, v103
	v_mul_f32_e32 v104, 0xbfb8aa3b, v104
	v_mul_f32_e32 v105, 0xbfb8aa3b, v105
	v_mul_f32_e32 v98, 0xbfb8aa3b, v98
	v_mul_f32_e32 v99, 0xbfb8aa3b, v99
	v_mul_f32_e32 v100, 0xbfb8aa3b, v100
	v_mul_f32_e32 v101, 0xbfb8aa3b, v101
	v_exp_f32_e32 v102, v102
	v_exp_f32_e32 v103, v103
	v_exp_f32_e32 v104, v104
	v_exp_f32_e32 v105, v105
	v_exp_f32_e32 v98, v98
	v_exp_f32_e32 v99, v99
	v_exp_f32_e32 v100, v100
	v_exp_f32_e32 v101, v101
	v_add_f32_e32 v102, 1.0, v102
	v_add_f32_e32 v103, 1.0, v103
	v_add_f32_e32 v104, 1.0, v104
	v_add_f32_e32 v105, 1.0, v105
	v_add_f32_e32 v98, 1.0, v98
	v_add_f32_e32 v99, 1.0, v99
	v_add_f32_e32 v100, 1.0, v100
	v_add_f32_e32 v101, 1.0, v101
	v_min_f32_e32 v102, 0x7149f2ca, v102
	v_min_f32_e32 v103, 0x7149f2ca, v103
	v_min_f32_e32 v104, 0x7149f2ca, v104
	v_min_f32_e32 v105, 0x7149f2ca, v105
	v_min_f32_e32 v98, 0x7149f2ca, v98
	v_min_f32_e32 v99, 0x7149f2ca, v99
	v_min_f32_e32 v100, 0x7149f2ca, v100
	v_min_f32_e32 v101, 0x7149f2ca, v101
	v_cvt_pk_bf16_f32 v102, v102, v103
	v_cvt_pk_bf16_f32 v103, v104, v105
	v_cvt_pk_bf16_f32 v104, v98, v99
	v_cvt_pk_bf16_f32 v105, v100, v101
	v_mul_f32_e32 v44, 0xbfb8aa3b, v44
	v_mul_f32_e32 v45, 0xbfb8aa3b, v45
	v_mul_f32_e32 v46, 0xbfb8aa3b, v46
	v_mul_f32_e32 v47, 0xbfb8aa3b, v47
	v_mul_f32_e32 v40, 0xbfb8aa3b, v40
	v_mul_f32_e32 v41, 0xbfb8aa3b, v41
	v_mul_f32_e32 v42, 0xbfb8aa3b, v42
	v_mul_f32_e32 v43, 0xbfb8aa3b, v43
	v_exp_f32_e32 v44, v44
	v_exp_f32_e32 v45, v45
	v_exp_f32_e32 v46, v46
	v_exp_f32_e32 v47, v47
	v_exp_f32_e32 v40, v40
	v_exp_f32_e32 v41, v41
	v_exp_f32_e32 v42, v42
	v_exp_f32_e32 v43, v43
	v_add_f32_e32 v44, 1.0, v44
	v_add_f32_e32 v45, 1.0, v45
	v_add_f32_e32 v46, 1.0, v46
	v_add_f32_e32 v47, 1.0, v47
	v_add_f32_e32 v40, 1.0, v40
	v_add_f32_e32 v41, 1.0, v41
	v_add_f32_e32 v42, 1.0, v42
	v_add_f32_e32 v43, 1.0, v43
	v_min_f32_e32 v44, 0x7149f2ca, v44
	v_min_f32_e32 v45, 0x7149f2ca, v45
	v_min_f32_e32 v46, 0x7149f2ca, v46
	v_min_f32_e32 v47, 0x7149f2ca, v47
	v_min_f32_e32 v40, 0x7149f2ca, v40
	v_min_f32_e32 v41, 0x7149f2ca, v41
	v_min_f32_e32 v42, 0x7149f2ca, v42
	v_min_f32_e32 v43, 0x7149f2ca, v43
	v_cvt_pk_bf16_f32 v44, v44, v45
	v_cvt_pk_bf16_f32 v45, v46, v47
	v_cvt_pk_bf16_f32 v46, v40, v41
	v_cvt_pk_bf16_f32 v47, v42, v43
	v_mul_f32_e32 v92, 0xbfb8aa3b, v92
	v_mul_f32_e32 v93, 0xbfb8aa3b, v93
	v_mul_f32_e32 v94, 0xbfb8aa3b, v94
	v_mul_f32_e32 v95, 0xbfb8aa3b, v95
	v_mul_f32_e32 v88, 0xbfb8aa3b, v88
	v_mul_f32_e32 v89, 0xbfb8aa3b, v89
	v_mul_f32_e32 v90, 0xbfb8aa3b, v90
	v_mul_f32_e32 v91, 0xbfb8aa3b, v91
	v_exp_f32_e32 v92, v92
	v_exp_f32_e32 v93, v93
	v_exp_f32_e32 v94, v94
	v_exp_f32_e32 v95, v95
	v_exp_f32_e32 v88, v88
	v_exp_f32_e32 v89, v89
	v_exp_f32_e32 v90, v90
	v_exp_f32_e32 v91, v91
	v_add_f32_e32 v92, 1.0, v92
	v_add_f32_e32 v93, 1.0, v93
	v_add_f32_e32 v94, 1.0, v94
	v_add_f32_e32 v95, 1.0, v95
	v_add_f32_e32 v88, 1.0, v88
	v_add_f32_e32 v89, 1.0, v89
	v_add_f32_e32 v90, 1.0, v90
	v_add_f32_e32 v91, 1.0, v91
	v_min_f32_e32 v92, 0x7149f2ca, v92
	v_min_f32_e32 v93, 0x7149f2ca, v93
	v_min_f32_e32 v94, 0x7149f2ca, v94
	v_min_f32_e32 v95, 0x7149f2ca, v95
	v_min_f32_e32 v88, 0x7149f2ca, v88
	v_min_f32_e32 v89, 0x7149f2ca, v89
	v_min_f32_e32 v90, 0x7149f2ca, v90
	v_min_f32_e32 v91, 0x7149f2ca, v91
	v_cvt_pk_bf16_f32 v92, v92, v93
	v_cvt_pk_bf16_f32 v93, v94, v95
; __device__ __forceinline__ float sigm(float v) { return __builtin_amdgcn_rcpf(1.0f + __builtin_amdgcn_exp2f(-LOG2E * v)); }
; __device__ __forceinline__ unsigned cvt_pk_bf16(float lo, float hi) { f32x2_t v = {lo, hi}; bf16x2_t b = __builtin_convertvector(v, bf16x2_t); return __builtin_bit_cast(unsigned, b); }
; #define EPI_FENCE() asm volatile("" ::: "memory")
; #define EPI_LANE() int t__ = threadIdx.x; asm volatile("" : "+v"(t__)); const int wid__ = __builtin_amdgcn_readfirstlane(t__ >> 6); wr = wid__ >> 2; wc = wid__ & 3; fr = t__ & 15; fq = (t__ & 63) >> 4
; template <int MODE> __device__ __forceinline__ float actf(float v) {
;     if (MODE == 1) return v * sigm(v);
;     if (MODE == 2) return fminf(1.0f + __builtin_amdgcn_exp2f(-LOG2E * v), 1e30f);
;     if (MODE == 3) return v * QSCALE;
;     return v;
; }
;     template <int MODE> __device__ __forceinline__ void run(const f32x4 (&acc)[2][2][4][2], const Unit& u, int wr, int wc, int fr, int fq) const {
;         EPI_LANE();
;         const int pn = u.pn, colt = pn * BM, t = colt >> 9;
;         char* base = (MODE == 2) ? (char*)(O + (size_t)6 * ((size_t)MTOK * 512)) + ((size_t)(((pn - 12) * 128 + u.pm) * 8 + wid__)) * 16384
;                                  : (char*)(O + (size_t)t * ((size_t)MTOK * 512) + (size_t)u.pm * BM * 512 + (colt & 511));
;         unsigned off0 = (MODE == 2) ? (unsigned)((t__ & 63) * 16) : (unsigned)((wr * 64 + fr) * 512 + wc * 32 + 8 * fq) * 2u; asm volatile("" : "+v"(off0));
; #pragma unroll
;         for (int bj = 0; bj < 2; ++bj) {
; #pragma unroll
;             for (int ai = 0; ai < 2; ++ai)
; #pragma unroll
;                 for (int m = 0; m < 4; ++m) { const unsigned off = off0 + ((MODE == 2) ? (unsigned)(((ai * 4 + m) * 2 + bj) * 1024) : (unsigned)((ai * HALF + m * 16) * 512 + bj * HALF) * 2u);
;                     const f32x4 v0 = acc[ai][bj][m][0], v1 = acc[ai][bj][m][1];
;                     u32x4 w; w.x = cvt_pk_bf16(actf<MODE>(v0[0]), actf<MODE>(v0[1])); w.y = cvt_pk_bf16(actf<MODE>(v0[2]), actf<MODE>(v0[3]));
;                     w.z = cvt_pk_bf16(actf<MODE>(v1[0]), actf<MODE>(v1[1])); w.w = cvt_pk_bf16(actf<MODE>(v1[2]), actf<MODE>(v1[3]));
;                     *(u32x4*)(base + off) = w; }
;             EPI_FENCE();
;         }
	v_cvt_pk_bf16_f32 v94, v88, v89
	v_cvt_pk_bf16_f32 v95, v90, v91
	v_mul_f32_e32 v36, 0xbfb8aa3b, v36
	v_mul_f32_e32 v37, 0xbfb8aa3b, v37
	v_mul_f32_e32 v38, 0xbfb8aa3b, v38
	v_mul_f32_e32 v39, 0xbfb8aa3b, v39
	v_mul_f32_e32 v32, 0xbfb8aa3b, v32
	v_mul_f32_e32 v33, 0xbfb8aa3b, v33
	v_mul_f32_e32 v34, 0xbfb8aa3b, v34
	v_mul_f32_e32 v35, 0xbfb8aa3b, v35
	v_exp_f32_e32 v36, v36
	v_exp_f32_e32 v37, v37
	v_exp_f32_e32 v38, v38
	v_exp_f32_e32 v39, v39
	v_exp_f32_e32 v32, v32
	v_exp_f32_e32 v33, v33
	v_exp_f32_e32 v34, v34
	v_exp_f32_e32 v35, v35
	v_add_f32_e32 v36, 1.0, v36
	v_add_f32_e32 v37, 1.0, v37
	v_add_f32_e32 v38, 1.0, v38
	v_add_f32_e32 v39, 1.0, v39
	v_add_f32_e32 v32, 1.0, v32
	v_add_f32_e32 v33, 1.0, v33
	v_add_f32_e32 v34, 1.0, v34
	v_add_f32_e32 v35, 1.0, v35
	v_min_f32_e32 v36, 0x7149f2ca, v36
	v_min_f32_e32 v37, 0x7149f2ca, v37
	v_min_f32_e32 v38, 0x7149f2ca, v38
	v_min_f32_e32 v39, 0x7149f2ca, v39
	v_min_f32_e32 v32, 0x7149f2ca, v32
	v_min_f32_e32 v33, 0x7149f2ca, v33
	v_min_f32_e32 v34, 0x7149f2ca, v34
	v_min_f32_e32 v35, 0x7149f2ca, v35
	v_cvt_pk_bf16_f32 v36, v36, v37
	v_cvt_pk_bf16_f32 v37, v38, v39
	v_cvt_pk_bf16_f32 v38, v32, v33
	v_cvt_pk_bf16_f32 v39, v34, v35
	v_mul_f32_e32 v84, 0xbfb8aa3b, v84
	v_mul_f32_e32 v85, 0xbfb8aa3b, v85
	v_mul_f32_e32 v86, 0xbfb8aa3b, v86
	v_mul_f32_e32 v87, 0xbfb8aa3b, v87
	v_mul_f32_e32 v80, 0xbfb8aa3b, v80
	v_mul_f32_e32 v81, 0xbfb8aa3b, v81
	v_mul_f32_e32 v82, 0xbfb8aa3b, v82
	v_mul_f32_e32 v83, 0xbfb8aa3b, v83
	v_exp_f32_e32 v84, v84
	v_exp_f32_e32 v85, v85
	v_exp_f32_e32 v86, v86
	v_exp_f32_e32 v87, v87
	v_exp_f32_e32 v80, v80
	v_exp_f32_e32 v81, v81
	v_exp_f32_e32 v82, v82
	v_exp_f32_e32 v83, v83
	v_add_f32_e32 v84, 1.0, v84
	v_add_f32_e32 v85, 1.0, v85
	v_add_f32_e32 v86, 1.0, v86
	v_add_f32_e32 v87, 1.0, v87
	v_add_f32_e32 v80, 1.0, v80
	v_add_f32_e32 v81, 1.0, v81
	v_add_f32_e32 v82, 1.0, v82
	v_add_f32_e32 v83, 1.0, v83
	v_min_f32_e32 v84, 0x7149f2ca, v84
	v_min_f32_e32 v85, 0x7149f2ca, v85
	v_min_f32_e32 v86, 0x7149f2ca, v86
	v_min_f32_e32 v87, 0x7149f2ca, v87
	v_min_f32_e32 v80, 0x7149f2ca, v80
	v_min_f32_e32 v81, 0x7149f2ca, v81
	v_min_f32_e32 v82, 0x7149f2ca, v82
	v_min_f32_e32 v83, 0x7149f2ca, v83
	v_cvt_pk_bf16_f32 v84, v84, v85
	v_cvt_pk_bf16_f32 v85, v86, v87
	v_cvt_pk_bf16_f32 v86, v80, v81
	v_cvt_pk_bf16_f32 v87, v82, v83
	v_mul_f32_e32 v28, 0xbfb8aa3b, v28
	v_mul_f32_e32 v29, 0xbfb8aa3b, v29
	v_mul_f32_e32 v30, 0xbfb8aa3b, v30
	v_mul_f32_e32 v31, 0xbfb8aa3b, v31
	v_mul_f32_e32 v24, 0xbfb8aa3b, v24
	v_mul_f32_e32 v25, 0xbfb8aa3b, v25
	v_mul_f32_e32 v26, 0xbfb8aa3b, v26
	v_mul_f32_e32 v27, 0xbfb8aa3b, v27
	v_exp_f32_e32 v28, v28
	v_exp_f32_e32 v29, v29
	v_exp_f32_e32 v30, v30
	v_exp_f32_e32 v31, v31
	v_exp_f32_e32 v24, v24
	v_exp_f32_e32 v25, v25
	v_exp_f32_e32 v26, v26
	v_exp_f32_e32 v27, v27
	v_add_f32_e32 v28, 1.0, v28
	v_add_f32_e32 v29, 1.0, v29
	v_add_f32_e32 v30, 1.0, v30
	v_add_f32_e32 v31, 1.0, v31
	v_add_f32_e32 v24, 1.0, v24
	v_add_f32_e32 v25, 1.0, v25
	v_add_f32_e32 v26, 1.0, v26
	v_add_f32_e32 v27, 1.0, v27
	v_min_f32_e32 v28, 0x7149f2ca, v28
	v_min_f32_e32 v29, 0x7149f2ca, v29
	v_min_f32_e32 v30, 0x7149f2ca, v30
	v_min_f32_e32 v31, 0x7149f2ca, v31
	v_min_f32_e32 v24, 0x7149f2ca, v24
	v_min_f32_e32 v25, 0x7149f2ca, v25
	v_min_f32_e32 v26, 0x7149f2ca, v26
	v_min_f32_e32 v27, 0x7149f2ca, v27
	v_cvt_pk_bf16_f32 v28, v28, v29
	v_cvt_pk_bf16_f32 v29, v30, v31
	v_cvt_pk_bf16_f32 v30, v24, v25
	v_cvt_pk_bf16_f32 v31, v26, v27
	v_mul_f32_e32 v76, 0xbfb8aa3b, v76
	v_mul_f32_e32 v77, 0xbfb8aa3b, v77
	v_mul_f32_e32 v78, 0xbfb8aa3b, v78
	v_mul_f32_e32 v79, 0xbfb8aa3b, v79
	v_mul_f32_e32 v72, 0xbfb8aa3b, v72
	v_mul_f32_e32 v73, 0xbfb8aa3b, v73
	v_mul_f32_e32 v74, 0xbfb8aa3b, v74
	v_mul_f32_e32 v75, 0xbfb8aa3b, v75
	v_exp_f32_e32 v76, v76
	v_exp_f32_e32 v77, v77
	v_exp_f32_e32 v78, v78
	v_exp_f32_e32 v79, v79
	v_exp_f32_e32 v72, v72
	v_exp_f32_e32 v73, v73
	v_exp_f32_e32 v74, v74
	v_exp_f32_e32 v75, v75
	v_add_f32_e32 v76, 1.0, v76
	v_add_f32_e32 v77, 1.0, v77
	v_add_f32_e32 v78, 1.0, v78
	v_add_f32_e32 v79, 1.0, v79
	v_add_f32_e32 v72, 1.0, v72
	v_add_f32_e32 v73, 1.0, v73
	v_add_f32_e32 v74, 1.0, v74
	v_add_f32_e32 v75, 1.0, v75
	v_min_f32_e32 v76, 0x7149f2ca, v76
	v_min_f32_e32 v77, 0x7149f2ca, v77
	v_min_f32_e32 v78, 0x7149f2ca, v78
	v_min_f32_e32 v79, 0x7149f2ca, v79
; __device__ __forceinline__ float sigm(float v) { return __builtin_amdgcn_rcpf(1.0f + __builtin_amdgcn_exp2f(-LOG2E * v)); }
; __device__ __forceinline__ unsigned cvt_pk_bf16(float lo, float hi) { f32x2_t v = {lo, hi}; bf16x2_t b = __builtin_convertvector(v, bf16x2_t); return __builtin_bit_cast(unsigned, b); }
; #define EPI_FENCE() asm volatile("" ::: "memory")
; #define EPI_LANE() int t__ = threadIdx.x; asm volatile("" : "+v"(t__)); const int wid__ = __builtin_amdgcn_readfirstlane(t__ >> 6); wr = wid__ >> 2; wc = wid__ & 3; fr = t__ & 15; fq = (t__ & 63) >> 4
; template <int MODE> __device__ __forceinline__ float actf(float v) {
;     if (MODE == 1) return v * sigm(v);
;     if (MODE == 2) return fminf(1.0f + __builtin_amdgcn_exp2f(-LOG2E * v), 1e30f);
;     if (MODE == 3) return v * QSCALE;
;     return v;
; }
;     template <int MODE> __device__ __forceinline__ void run(const f32x4 (&acc)[2][2][4][2], const Unit& u, int wr, int wc, int fr, int fq) const {
;         EPI_LANE();
;         const int pn = u.pn, colt = pn * BM, t = colt >> 9;
;         char* base = (MODE == 2) ? (char*)(O + (size_t)6 * ((size_t)MTOK * 512)) + ((size_t)(((pn - 12) * 128 + u.pm) * 8 + wid__)) * 16384
;                                  : (char*)(O + (size_t)t * ((size_t)MTOK * 512) + (size_t)u.pm * BM * 512 + (colt & 511));
;         unsigned off0 = (MODE == 2) ? (unsigned)((t__ & 63) * 16) : (unsigned)((wr * 64 + fr) * 512 + wc * 32 + 8 * fq) * 2u; asm volatile("" : "+v"(off0));
; #pragma unroll
;         for (int bj = 0; bj < 2; ++bj) {
; #pragma unroll
;             for (int ai = 0; ai < 2; ++ai)
; #pragma unroll
;                 for (int m = 0; m < 4; ++m) { const unsigned off = off0 + ((MODE == 2) ? (unsigned)(((ai * 4 + m) * 2 + bj) * 1024) : (unsigned)((ai * HALF + m * 16) * 512 + bj * HALF) * 2u);
;                     const f32x4 v0 = acc[ai][bj][m][0], v1 = acc[ai][bj][m][1];
;                     u32x4 w; w.x = cvt_pk_bf16(actf<MODE>(v0[0]), actf<MODE>(v0[1])); w.y = cvt_pk_bf16(actf<MODE>(v0[2]), actf<MODE>(v0[3]));
;                     w.z = cvt_pk_bf16(actf<MODE>(v1[0]), actf<MODE>(v1[1])); w.w = cvt_pk_bf16(actf<MODE>(v1[2]), actf<MODE>(v1[3]));
;                     *(u32x4*)(base + off) = w; }
;             EPI_FENCE();
;         }
	v_min_f32_e32 v72, 0x7149f2ca, v72
	v_min_f32_e32 v73, 0x7149f2ca, v73
	v_min_f32_e32 v74, 0x7149f2ca, v74
	v_min_f32_e32 v75, 0x7149f2ca, v75
	v_cvt_pk_bf16_f32 v76, v76, v77
	v_cvt_pk_bf16_f32 v77, v78, v79
	v_cvt_pk_bf16_f32 v78, v72, v73
	v_cvt_pk_bf16_f32 v79, v74, v75
	v_mul_f32_e32 v20, 0xbfb8aa3b, v20
	v_mul_f32_e32 v21, 0xbfb8aa3b, v21
	v_mul_f32_e32 v22, 0xbfb8aa3b, v22
	v_mul_f32_e32 v23, 0xbfb8aa3b, v23
	v_mul_f32_e32 v16, 0xbfb8aa3b, v16
	v_mul_f32_e32 v17, 0xbfb8aa3b, v17
	v_mul_f32_e32 v18, 0xbfb8aa3b, v18
	v_mul_f32_e32 v19, 0xbfb8aa3b, v19
	v_exp_f32_e32 v20, v20
	v_exp_f32_e32 v21, v21
	v_exp_f32_e32 v22, v22
	v_exp_f32_e32 v23, v23
	v_exp_f32_e32 v16, v16
	v_exp_f32_e32 v17, v17
	v_exp_f32_e32 v18, v18
	v_exp_f32_e32 v19, v19
	v_add_f32_e32 v20, 1.0, v20
	v_add_f32_e32 v21, 1.0, v21
	v_add_f32_e32 v22, 1.0, v22
	v_add_f32_e32 v23, 1.0, v23
	v_add_f32_e32 v16, 1.0, v16
	v_add_f32_e32 v17, 1.0, v17
	v_add_f32_e32 v18, 1.0, v18
	v_add_f32_e32 v19, 1.0, v19
	v_min_f32_e32 v20, 0x7149f2ca, v20
	v_min_f32_e32 v21, 0x7149f2ca, v21
	v_min_f32_e32 v22, 0x7149f2ca, v22
	v_min_f32_e32 v23, 0x7149f2ca, v23
	v_min_f32_e32 v16, 0x7149f2ca, v16
	v_min_f32_e32 v17, 0x7149f2ca, v17
	v_min_f32_e32 v18, 0x7149f2ca, v18
	v_min_f32_e32 v19, 0x7149f2ca, v19
	v_cvt_pk_bf16_f32 v20, v20, v21
	v_cvt_pk_bf16_f32 v21, v22, v23
	v_cvt_pk_bf16_f32 v22, v16, v17
	v_cvt_pk_bf16_f32 v23, v18, v19
	v_mul_f32_e32 v12, 0xbfb8aa3b, v12
	v_mul_f32_e32 v13, 0xbfb8aa3b, v13
	v_mul_f32_e32 v14, 0xbfb8aa3b, v14
	v_mul_f32_e32 v15, 0xbfb8aa3b, v15
	v_mul_f32_e32 v8, 0xbfb8aa3b, v8
	v_mul_f32_e32 v9, 0xbfb8aa3b, v9
	v_mul_f32_e32 v10, 0xbfb8aa3b, v10
	v_mul_f32_e32 v11, 0xbfb8aa3b, v11
	v_exp_f32_e32 v12, v12
	v_exp_f32_e32 v13, v13
	v_exp_f32_e32 v14, v14
	v_exp_f32_e32 v15, v15
	v_exp_f32_e32 v8, v8
	v_exp_f32_e32 v9, v9
	v_exp_f32_e32 v10, v10
	v_exp_f32_e32 v11, v11
	v_add_f32_e32 v12, 1.0, v12
	v_add_f32_e32 v13, 1.0, v13
	v_add_f32_e32 v14, 1.0, v14
	v_add_f32_e32 v15, 1.0, v15
	v_add_f32_e32 v8, 1.0, v8
	v_add_f32_e32 v9, 1.0, v9
	v_add_f32_e32 v10, 1.0, v10
	v_add_f32_e32 v11, 1.0, v11
	v_min_f32_e32 v12, 0x7149f2ca, v12
	v_min_f32_e32 v13, 0x7149f2ca, v13
	v_min_f32_e32 v14, 0x7149f2ca, v14
	v_min_f32_e32 v15, 0x7149f2ca, v15
	v_min_f32_e32 v8, 0x7149f2ca, v8
	v_min_f32_e32 v9, 0x7149f2ca, v9
	v_min_f32_e32 v10, 0x7149f2ca, v10
	v_min_f32_e32 v11, 0x7149f2ca, v11
	v_cvt_pk_bf16_f32 v12, v12, v13
	v_cvt_pk_bf16_f32 v13, v14, v15
	v_cvt_pk_bf16_f32 v14, v8, v9
	v_cvt_pk_bf16_f32 v15, v10, v11
	v_mul_f32_e32 v4, 0xbfb8aa3b, v4
	v_mul_f32_e32 v5, 0xbfb8aa3b, v5
	v_mul_f32_e32 v6, 0xbfb8aa3b, v6
	v_mul_f32_e32 v7, 0xbfb8aa3b, v7
	v_mul_f32_e32 v0, 0xbfb8aa3b, v0
	v_mul_f32_e32 v1, 0xbfb8aa3b, v1
	v_mul_f32_e32 v2, 0xbfb8aa3b, v2
	v_mul_f32_e32 v3, 0xbfb8aa3b, v3
	v_exp_f32_e32 v4, v4
	v_exp_f32_e32 v5, v5
	v_exp_f32_e32 v6, v6
	v_exp_f32_e32 v7, v7
	v_exp_f32_e32 v0, v0
	v_exp_f32_e32 v1, v1
	v_exp_f32_e32 v2, v2
	v_exp_f32_e32 v3, v3
	v_add_f32_e32 v4, 1.0, v4
	v_add_f32_e32 v5, 1.0, v5
	v_add_f32_e32 v6, 1.0, v6
	v_add_f32_e32 v7, 1.0, v7
	v_add_f32_e32 v0, 1.0, v0
	v_add_f32_e32 v1, 1.0, v1
	v_add_f32_e32 v2, 1.0, v2
	v_add_f32_e32 v3, 1.0, v3
	v_min_f32_e32 v4, 0x7149f2ca, v4
	v_min_f32_e32 v5, 0x7149f2ca, v5
	v_min_f32_e32 v6, 0x7149f2ca, v6
	v_min_f32_e32 v7, 0x7149f2ca, v7
	v_min_f32_e32 v0, 0x7149f2ca, v0
	v_min_f32_e32 v1, 0x7149f2ca, v1
	v_min_f32_e32 v2, 0x7149f2ca, v2
	v_min_f32_e32 v3, 0x7149f2ca, v3
	v_cvt_pk_bf16_f32 v4, v4, v5
	v_cvt_pk_bf16_f32 v5, v6, v7
	v_cvt_pk_bf16_f32 v6, v0, v1
	v_cvt_pk_bf16_f32 v7, v2, v3
	global_store_dwordx4 v142, v[126:129], s[54:55]
	global_store_dwordx4 v144, v[68:71], s[54:55]
	global_store_dwordx4 v145, v[118:121], s[54:55]
	global_store_dwordx4 v146, v[60:63], s[54:55]
	global_store_dwordx4 v147, v[110:113], s[54:55]
	global_store_dwordx4 v148, v[52:55], s[54:55]
	global_store_dwordx4 v149, v[102:105], s[54:55]
	global_store_dwordx4 v150, v[44:47], s[54:55]
	global_store_dwordx4 v151, v[92:95], s[54:55]
	global_store_dwordx4 v152, v[36:39], s[54:55]
	global_store_dwordx4 v153, v[84:87], s[54:55]
	global_store_dwordx4 v154, v[28:31], s[54:55]
	global_store_dwordx4 v155, v[76:79], s[54:55]
	global_store_dwordx4 v156, v[20:23], s[54:55]
	global_store_dwordx4 v157, v[12:15], s[54:55]
	global_store_dwordx4 v158, v[4:7], s[54:55]
